# v67 + 8 more attention f32->bf16 RNE bit-trick packs replaced by v_cvt_pk_bf16_f32 (33 of 40 now)
# speedup vs baseline: 1.0053x; 1.0005x over previous
; #define EXP2(x) __builtin_amdgcn_exp2f(x)
; #define SHFL_XOR3(v, m, lane) shfl_from((v), (lane) ^ (m))
; DEV void attn_compute(const AttnU& a, const bf16x8 (&qf)[4], int tq, bf16_t* OG, float* LSE, LAS unsigned char* lds, int tid) {
;     ...
;     mx = fmaxf(mx, SHFL_XOR3(mx, 32, lane));
;     float rs = 0.f;
; #pragma unroll
;     for (int sb = 0; sb < 5; ++sb)
; #pragma unroll
;         for (int rg = 0; rg < 16; ++rg) { const float p = EXP2(s[sb][rg] - mx); s[sb][rg] = p; rs += p; }
.LBB0_821:
	s_mov_b32 s29, 0xf149f2ca
	v_max3_f32 v3, v49, s29, v48
	v_max3_f32 v3, v3, v51, v50
	v_max3_f32 v3, v3, v70, v52
	v_max3_f32 v3, v3, v73, v72
	v_max3_f32 v3, v3, v75, v74
	v_max3_f32 v3, v3, v77, v76
	v_max3_f32 v3, v3, v80, v79
	v_max3_f32 v3, v3, v82, v81
	v_max3_f32 v3, v3, v84, v83
	v_max3_f32 v3, v3, v86, v85
	v_max3_f32 v3, v3, v88, v87
	v_max3_f32 v3, v3, v90, v89
	v_max3_f32 v3, v3, v92, v91
	v_max3_f32 v3, v3, v94, v93
	v_max3_f32 v3, v3, v96, v95
	v_max3_f32 v3, v3, v98, v97
	v_max3_f32 v3, v3, v100, v99
	v_max3_f32 v3, v3, v102, v101
	v_max3_f32 v3, v3, v104, v103
	v_max3_f32 v3, v3, v106, v105
	v_max3_f32 v3, v3, v108, v107
	v_max3_f32 v3, v3, v153, v109
	v_max3_f32 v3, v3, v155, v154
	v_max3_f32 v3, v3, v157, v156
	v_max3_f32 v3, v3, v159, v158
	v_max3_f32 v3, v3, v161, v160
	v_max3_f32 v3, v3, v163, v162
	v_max3_f32 v3, v3, v165, v164
	v_max3_f32 v3, v3, v187, v166
	v_max3_f32 v3, v3, v193, v192
	v_max3_f32 v3, v3, v196, v195
	v_max3_f32 v3, v3, v204, v201
	v_max3_f32 v3, v3, v54, v46
	v_max3_f32 v3, v3, v1, v0
	v_max3_f32 v3, v3, v56, v55
	v_max3_f32 v3, v3, v5, v4
	v_max3_f32 v3, v3, v7, v6
	v_and_b32_e32 v2, 63, v146
	v_max3_f32 v3, v3, v9, v8
	v_max3_f32 v3, v3, v11, v10
	v_lshlrev_b32_e32 v12, 2, v2
	v_max3_f32 v3, v3, v58, v57
	v_xor_b32_e32 v53, 0x80, v12
	ds_bpermute_b32 v12, v53, v3
	v_mov_b32_e32 v78, 0
	v_mov_b32_e32 v59, 0
	v_mov_b32_e32 v60, 0
	v_mov_b32_e32 v61, 0
	s_waitcnt lgkmcnt(0)
	v_max_f32_e32 v12, v12, v12
	v_max_f32_e32 v3, v3, v12
	v_sub_f32_e32 v12, v49, v3
	v_exp_f32_e32 v223, v12
	v_sub_f32_e32 v12, v48, v3
	v_exp_f32_e32 v225, v12
	v_sub_f32_e32 v12, v51, v3
	v_exp_f32_e32 v224, v12
	v_sub_f32_e32 v12, v50, v3
	v_exp_f32_e32 v227, v12
	v_sub_f32_e32 v13, v70, v3
	v_add_f32_e32 v12, 0, v223
	v_exp_f32_e32 v226, v13
	v_sub_f32_e32 v13, v52, v3
	v_add_f32_e32 v12, v225, v12
	v_exp_f32_e32 v229, v13
	v_sub_f32_e32 v13, v73, v3
	v_add_f32_e32 v12, v224, v12
	v_exp_f32_e32 v228, v13
	v_sub_f32_e32 v13, v72, v3
	v_add_f32_e32 v12, v227, v12
	v_exp_f32_e32 v230, v13
	v_sub_f32_e32 v13, v75, v3
	v_add_f32_e32 v12, v226, v12
	v_exp_f32_e32 v215, v13
	v_sub_f32_e32 v13, v74, v3
	v_add_f32_e32 v12, v229, v12
	v_exp_f32_e32 v217, v13
	v_sub_f32_e32 v13, v77, v3
	v_add_f32_e32 v12, v228, v12
	v_exp_f32_e32 v216, v13
	v_sub_f32_e32 v13, v76, v3
	v_add_f32_e32 v12, v230, v12
	v_exp_f32_e32 v219, v13
	v_sub_f32_e32 v13, v80, v3
	v_add_f32_e32 v12, v215, v12
	v_exp_f32_e32 v218, v13
	v_sub_f32_e32 v13, v79, v3
	v_add_f32_e32 v12, v217, v12
	v_exp_f32_e32 v221, v13
	v_sub_f32_e32 v13, v82, v3
	v_add_f32_e32 v12, v216, v12
	v_exp_f32_e32 v220, v13
	v_sub_f32_e32 v13, v81, v3
	v_add_f32_e32 v12, v219, v12
	v_exp_f32_e32 v222, v13
	v_sub_f32_e32 v13, v84, v3
	v_add_f32_e32 v12, v218, v12
	v_exp_f32_e32 v208, v13
	v_sub_f32_e32 v13, v83, v3
	v_add_f32_e32 v12, v221, v12
	v_exp_f32_e32 v207, v13
	v_sub_f32_e32 v13, v86, v3
	v_add_f32_e32 v12, v220, v12
	v_exp_f32_e32 v209, v13
	v_sub_f32_e32 v13, v85, v3
	v_add_f32_e32 v12, v222, v12
	v_exp_f32_e32 v211, v13
	v_sub_f32_e32 v13, v88, v3
	v_add_f32_e32 v12, v208, v12
	v_exp_f32_e32 v210, v13
	v_sub_f32_e32 v13, v87, v3
	v_add_f32_e32 v12, v207, v12
	v_exp_f32_e32 v213, v13
	v_sub_f32_e32 v13, v90, v3
	v_add_f32_e32 v12, v209, v12
	v_exp_f32_e32 v212, v13
	v_sub_f32_e32 v13, v89, v3
	v_add_f32_e32 v12, v211, v12
	v_exp_f32_e32 v214, v13
	v_sub_f32_e32 v13, v92, v3
	v_add_f32_e32 v12, v210, v12
	v_exp_f32_e32 v194, v13
	v_sub_f32_e32 v13, v91, v3
	v_add_f32_e32 v12, v213, v12
	v_exp_f32_e32 v198, v13
	v_sub_f32_e32 v13, v94, v3
	v_add_f32_e32 v12, v212, v12
	v_exp_f32_e32 v197, v13
	v_sub_f32_e32 v13, v93, v3
	v_add_f32_e32 v12, v214, v12
	v_exp_f32_e32 v200, v13
	v_sub_f32_e32 v13, v96, v3
	v_add_f32_e32 v12, v194, v12
	v_exp_f32_e32 v199, v13
	v_sub_f32_e32 v13, v95, v3
	v_add_f32_e32 v12, v198, v12
	v_exp_f32_e32 v203, v13
	v_sub_f32_e32 v13, v98, v3
	v_add_f32_e32 v12, v197, v12
	v_exp_f32_e32 v202, v13
	v_sub_f32_e32 v13, v97, v3
	v_add_f32_e32 v12, v200, v12
	v_exp_f32_e32 v205, v13
	v_sub_f32_e32 v13, v100, v3
	v_add_f32_e32 v12, v199, v12
	v_exp_f32_e32 v183, v13
	v_sub_f32_e32 v13, v99, v3
	v_add_f32_e32 v12, v203, v12
	v_exp_f32_e32 v185, v13
	v_sub_f32_e32 v13, v102, v3
	v_add_f32_e32 v12, v202, v12
	v_exp_f32_e32 v184, v13
	v_sub_f32_e32 v13, v101, v3
	v_add_f32_e32 v12, v205, v12
	v_exp_f32_e32 v188, v13
	v_sub_f32_e32 v13, v104, v3
	v_add_f32_e32 v12, v183, v12
	v_exp_f32_e32 v186, v13
	v_sub_f32_e32 v13, v103, v3
	v_add_f32_e32 v12, v185, v12
	v_exp_f32_e32 v190, v13
	v_sub_f32_e32 v13, v106, v3
	v_add_f32_e32 v12, v184, v12
	v_exp_f32_e32 v189, v13
	v_sub_f32_e32 v13, v105, v3
	v_add_f32_e32 v12, v188, v12
	v_exp_f32_e32 v191, v13
	v_sub_f32_e32 v13, v108, v3
	v_add_f32_e32 v12, v186, v12
	v_exp_f32_e32 v175, v13
	v_sub_f32_e32 v13, v107, v3
	v_add_f32_e32 v12, v190, v12
	v_exp_f32_e32 v177, v13
	v_sub_f32_e32 v13, v153, v3
	v_add_f32_e32 v12, v189, v12
	v_exp_f32_e32 v176, v13
	v_sub_f32_e32 v13, v109, v3
	v_add_f32_e32 v12, v191, v12
	v_exp_f32_e32 v179, v13
	v_sub_f32_e32 v13, v155, v3
	v_add_f32_e32 v12, v175, v12
	v_exp_f32_e32 v178, v13
	v_sub_f32_e32 v13, v154, v3
	v_add_f32_e32 v12, v177, v12
	v_exp_f32_e32 v181, v13
	v_sub_f32_e32 v13, v157, v3
	v_add_f32_e32 v12, v176, v12
	v_exp_f32_e32 v180, v13
	v_sub_f32_e32 v13, v156, v3
	v_add_f32_e32 v12, v179, v12
	v_exp_f32_e32 v182, v13
	v_sub_f32_e32 v13, v159, v3
	v_add_f32_e32 v12, v178, v12
	v_exp_f32_e32 v167, v13
	v_sub_f32_e32 v13, v158, v3
	v_add_f32_e32 v12, v181, v12
	v_exp_f32_e32 v169, v13
	v_sub_f32_e32 v13, v161, v3
	v_add_f32_e32 v12, v180, v12
	v_exp_f32_e32 v168, v13
; #define LAS __attribute__((address_space(3)))
; #define EXP2(x) __builtin_amdgcn_exp2f(x)
; #define SHFL_XOR3(v, m, lane) shfl_from((v), (lane) ^ (m))
; #define MFMA32(a, b, c) __builtin_amdgcn_mfma_f32_32x32x16_bf16((a), (b), (c), 0, 0, 0)
; DEV unsigned pk2(float lo, float hi) { return (unsigned)f2bf(lo) | ((unsigned)f2bf(hi) << 16); }
; DEV void attn_compute(const AttnU& a, const bf16x8 (&qf)[4], int tq, bf16_t* OG, float* LSE, LAS unsigned char* lds, int tid) {
;     ...
;     for (int sb = 0; sb < 5; ++sb)
; #pragma unroll
;         for (int rg = 0; rg < 16; ++rg) { const float p = EXP2(s[sb][rg] - mx); s[sb][rg] = p; rs += p; }
;     rs += SHFL_XOR3(rs, 32, lane);
;     f32x16 oacc[2];
; #pragma unroll
;     for (int eb = 0; eb < 2; ++eb)
; #pragma unroll
;         for (int i = 0; i < 16; ++i) oacc[eb][i] = 0.f;
; #pragma unroll
;     for (int sb = 0; sb < 5; ++sb) {
;         if (!vb[sb]) continue;
; #pragma unroll
;         for (int s2 = 0; s2 < 2; ++s2) {
;             u32x4 w;
;             w.x = pk2(s[sb][8 * s2 + 0], s[sb][8 * s2 + 1]); w.y = pk2(s[sb][8 * s2 + 2], s[sb][8 * s2 + 3]);
;             w.z = pk2(s[sb][8 * s2 + 4], s[sb][8 * s2 + 5]); w.w = pk2(s[sb][8 * s2 + 6], s[sb][8 * s2 + 7]);
;             const bf16x8 pf = BITCAST(bf16x8, w);
; #pragma unroll
;             for (int eb = 0; eb < 2; ++eb) {
;                 const LAS unsigned char* vp = lds + AT_V_OFF + (32 * eb + n) * AT_VP + (32 * (wave + sb) + 16 * s2 + 4 * hl) * 2;
;                 const u32x2 lo = *(const LAS u32x2*)vp, hi = *(const LAS u32x2*)(vp + 16);
;                 u32x4 wv; wv.x = lo.x; wv.y = lo.y; wv.z = hi.x; wv.w = hi.y;
;                 oacc[eb] = MFMA32(BITCAST(bf16x8, wv), pf, oacc[eb]);
;             }
	v_sub_f32_e32 v13, v160, v3
	v_add_f32_e32 v12, v182, v12
	v_exp_f32_e32 v171, v13
	v_sub_f32_e32 v13, v163, v3
	v_add_f32_e32 v12, v167, v12
	v_exp_f32_e32 v170, v13
	v_sub_f32_e32 v13, v162, v3
	v_add_f32_e32 v12, v169, v12
	v_exp_f32_e32 v173, v13
	v_sub_f32_e32 v13, v165, v3
	v_add_f32_e32 v12, v168, v12
	v_exp_f32_e32 v172, v13
	v_sub_f32_e32 v13, v164, v3
	v_add_f32_e32 v12, v171, v12
	v_exp_f32_e32 v174, v13
	v_sub_f32_e32 v13, v187, v3
	v_add_f32_e32 v12, v170, v12
	v_exp_f32_e32 v159, v13
	v_sub_f32_e32 v13, v166, v3
	v_add_f32_e32 v12, v173, v12
	v_exp_f32_e32 v161, v13
	v_sub_f32_e32 v13, v193, v3
	v_add_f32_e32 v12, v172, v12
	v_exp_f32_e32 v160, v13
	v_sub_f32_e32 v13, v192, v3
	v_add_f32_e32 v12, v174, v12
	v_exp_f32_e32 v163, v13
	v_sub_f32_e32 v13, v196, v3
	v_add_f32_e32 v12, v159, v12
	v_exp_f32_e32 v162, v13
	v_sub_f32_e32 v13, v195, v3
	v_add_f32_e32 v12, v161, v12
	v_exp_f32_e32 v165, v13
	v_sub_f32_e32 v13, v204, v3
	v_add_f32_e32 v12, v160, v12
	v_exp_f32_e32 v164, v13
	v_sub_f32_e32 v13, v201, v3
	v_add_f32_e32 v12, v163, v12
	v_exp_f32_e32 v166, v13
	v_add_f32_e32 v12, v162, v12
	v_add_f32_e32 v12, v165, v12
	v_add_f32_e32 v12, v164, v12
	v_add_f32_e32 v15, v166, v12
	v_sub_f32_e32 v12, v54, v3
	v_exp_f32_e32 v12, v12
	v_sub_f32_e32 v13, v46, v3
	v_exp_f32_e32 v14, v13
	v_sub_f32_e32 v1, v1, v3
	v_exp_f32_e32 v13, v1
	v_sub_f32_e32 v0, v0, v3
	v_exp_f32_e32 v153, v0
	v_sub_f32_e32 v1, v56, v3
	v_add_f32_e32 v0, v12, v15
	v_exp_f32_e32 v15, v1
	v_sub_f32_e32 v1, v55, v3
	v_add_f32_e32 v0, v14, v0
	v_exp_f32_e32 v155, v1
	v_sub_f32_e32 v1, v5, v3
	v_add_f32_e32 v0, v13, v0
	v_exp_f32_e32 v154, v1
	v_sub_f32_e32 v1, v4, v3
	v_add_f32_e32 v0, v153, v0
	v_exp_f32_e32 v156, v1
	v_sub_f32_e32 v1, v7, v3
	v_add_f32_e32 v0, v15, v0
	v_exp_f32_e32 v4, v1
	v_sub_f32_e32 v1, v6, v3
	v_add_f32_e32 v0, v155, v0
	v_exp_f32_e32 v6, v1
	v_sub_f32_e32 v1, v9, v3
	v_add_f32_e32 v0, v154, v0
	v_exp_f32_e32 v5, v1
	v_sub_f32_e32 v1, v8, v3
	v_add_f32_e32 v0, v156, v0
	v_exp_f32_e32 v8, v1
	v_sub_f32_e32 v1, v11, v3
	v_add_f32_e32 v0, v4, v0
	v_exp_f32_e32 v7, v1
	v_sub_f32_e32 v1, v10, v3
	v_add_f32_e32 v0, v6, v0
	v_exp_f32_e32 v10, v1
	v_sub_f32_e32 v1, v58, v3
	v_add_f32_e32 v0, v5, v0
	v_exp_f32_e32 v9, v1
	v_sub_f32_e32 v1, v57, v3
	v_add_f32_e32 v0, v8, v0
	v_exp_f32_e32 v11, v1
	v_add_f32_e32 v0, v7, v0
	v_add_f32_e32 v0, v10, v0
	v_add_f32_e32 v0, v9, v0
	v_add_f32_e32 v0, v11, v0
	ds_bpermute_b32 v1, v53, v0
	v_lshl_add_u32 v157, v47, 3, 0
	v_mul_u32_u24_e32 v158, 0x308, v147
	v_mov_b32_e32 v79, 0
	v_mov_b32_e32 v80, 0
	v_mov_b32_e32 v81, 0
	v_mov_b32_e32 v82, 0
	v_mov_b32_e32 v83, 0
	v_mov_b32_e32 v84, 0
	v_mov_b32_e32 v85, 0
	v_mov_b32_e32 v86, 0
	v_mov_b32_e32 v87, 0
	v_mov_b32_e32 v88, 0
	v_mov_b32_e32 v89, 0
	v_mov_b32_e32 v90, 0
	v_mov_b32_e32 v91, 0
	v_mov_b32_e32 v92, 0
	v_mov_b32_e32 v93, 0
	v_mov_b32_e32 v94, 0
	v_mov_b32_e32 v95, 0
	v_mov_b32_e32 v96, 0
	v_mov_b32_e32 v97, 0
	v_mov_b32_e32 v98, 0
	v_mov_b32_e32 v99, 0
	v_mov_b32_e32 v100, 0
	v_mov_b32_e32 v101, 0
	v_mov_b32_e32 v102, 0
	v_mov_b32_e32 v103, 0
	v_mov_b32_e32 v104, 0
	v_mov_b32_e32 v105, 0
	v_mov_b32_e32 v106, 0
	v_mov_b32_e32 v107, 0
	v_mov_b32_e32 v108, 0
	v_mov_b32_e32 v109, 0
	v_mov_b32_e32 v46, 0
	v_mov_b32_e32 v47, 0
	v_mov_b32_e32 v48, 0
	v_mov_b32_e32 v49, 0
	v_mov_b32_e32 v50, 0
	v_mov_b32_e32 v51, 0
	v_mov_b32_e32 v52, 0
	v_mov_b32_e32 v53, 0
	v_mov_b32_e32 v54, 0
	v_mov_b32_e32 v55, 0
	v_mov_b32_e32 v56, 0
	v_mov_b32_e32 v57, 0
	v_mov_b32_e32 v58, 0
	v_mov_b32_e32 v62, 0
	v_mov_b32_e32 v63, 0
	v_mov_b32_e32 v64, 0
	v_mov_b32_e32 v65, 0
	v_mov_b32_e32 v66, 0
	v_mov_b32_e32 v67, 0
	v_mov_b32_e32 v68, 0
	v_mov_b32_e32 v69, 0
	v_mov_b32_e32 v70, 0
	v_mov_b32_e32 v71, 0
	v_mov_b32_e32 v72, 0
	v_mov_b32_e32 v73, 0
	v_mov_b32_e32 v74, 0
	v_mov_b32_e32 v75, 0
	v_mov_b32_e32 v76, 0
	v_mov_b32_e32 v77, 0
	s_and_saveexec_b64 s[42:43], s[2:3]
	s_cbranch_execz .LBB0_829
	v_and_b32_e32 v46, 0xffffffc0, v146
	v_add3_u32 v58, v157, v46, v158
	v_add_u32_e32 v59, 0xd800, v58
	ds_read2_b64 v[46:49], v59 offset1:2
	s_mov_b32 s2, 0xffff0000
	v_cvt_pk_bf16_f32 v53, v228, v230
	v_cvt_pk_bf16_f32 v52, v226, v229
	v_cvt_pk_bf16_f32 v51, v224, v227
	v_cvt_pk_bf16_f32 v50, v223, v225
	s_waitcnt lgkmcnt(0)
	s_nop 0
	v_mfma_f32_32x32x16_bf16 v[78:93], v[46:49], v[50:53], 0
	v_add_u32_e32 v46, 0x6100, v58
	v_add_u32_e32 v58, 0xd800, v46
	ds_read2_b64 v[46:49], v58 offset1:2
	ds_read2_b64 v[54:57], v59 offset0:4 offset1:6
	s_waitcnt lgkmcnt(1)
	v_mfma_f32_32x32x16_bf16 v[94:109], v[46:49], v[50:53], 0
	v_cvt_pk_bf16_f32 v49, v220, v222
	v_cvt_pk_bf16_f32 v48, v218, v221
	v_cvt_pk_bf16_f32 v47, v216, v219
	v_cvt_pk_bf16_f32 v46, v215, v217
	ds_read2_b64 v[50:53], v58 offset0:4 offset1:6
	s_waitcnt lgkmcnt(1)
	v_mfma_f32_32x32x16_bf16 v[78:93], v[54:57], v[46:49], v[78:93]
	s_waitcnt lgkmcnt(0)
	v_mfma_f32_32x32x16_bf16 v[94:109], v[50:53], v[46:49], v[94:109]
	s_nop 9
	v_mov_b32_e32 v46, v78
	v_mov_b32_e32 v47, v79
	v_mov_b32_e32 v48, v80
	v_mov_b32_e32 v49, v81
	v_mov_b32_e32 v50, v82
	v_mov_b32_e32 v51, v83
	v_mov_b32_e32 v52, v84
	v_mov_b32_e32 v53, v85
	v_mov_b32_e32 v54, v86
	v_mov_b32_e32 v55, v87
	v_mov_b32_e32 v56, v88
	v_mov_b32_e32 v57, v89
	v_mov_b32_e32 v58, v90
	v_mov_b32_e32 v59, v91
	v_mov_b32_e32 v60, v92
	v_mov_b32_e32 v61, v93
	v_mov_b32_e32 v62, v94
	v_mov_b32_e32 v63, v95
	v_mov_b32_e32 v64, v96
	v_mov_b32_e32 v65, v97
	v_mov_b32_e32 v66, v98
	v_mov_b32_e32 v67, v99
	v_mov_b32_e32 v68, v100
	v_mov_b32_e32 v69, v101
	v_mov_b32_e32 v70, v102
	v_mov_b32_e32 v71, v103
	v_mov_b32_e32 v72, v104
	v_mov_b32_e32 v73, v105
	v_mov_b32_e32 v74, v106
	v_mov_b32_e32 v75, v107
	v_mov_b32_e32 v76, v108
	v_mov_b32_e32 v77, v109
	s_or_b64 exec, exec, s[42:43]
	s_and_saveexec_b64 s[2:3], s[6:7]
	s_cbranch_execnz .LBB0_830

; #define LAS __attribute__((address_space(3)))
; #define MFMA32(a, b, c) __builtin_amdgcn_mfma_f32_32x32x16_bf16((a), (b), (c), 0, 0, 0)
; DEV unsigned pk2(float lo, float hi) { return (unsigned)f2bf(lo) | ((unsigned)f2bf(hi) << 16); }
; DEV void attn_compute(const AttnU& a, const bf16x8 (&qf)[4], int tq, bf16_t* OG, float* LSE, LAS unsigned char* lds, int tid) {
;     ...
;     for (int sb = 0; sb < 5; ++sb) {
;         if (!vb[sb]) continue;
; #pragma unroll
;         for (int s2 = 0; s2 < 2; ++s2) {
;             u32x4 w;
;             w.x = pk2(s[sb][8 * s2 + 0], s[sb][8 * s2 + 1]); w.y = pk2(s[sb][8 * s2 + 2], s[sb][8 * s2 + 3]);
;             w.z = pk2(s[sb][8 * s2 + 4], s[sb][8 * s2 + 5]); w.w = pk2(s[sb][8 * s2 + 6], s[sb][8 * s2 + 7]);
;             const bf16x8 pf = BITCAST(bf16x8, w);
; #pragma unroll
;             for (int eb = 0; eb < 2; ++eb) {
;                 const LAS unsigned char* vp = lds + AT_V_OFF + (32 * eb + n) * AT_VP + (32 * (wave + sb) + 16 * s2 + 4 * hl) * 2;
;                 const u32x2 lo = *(const LAS u32x2*)vp, hi = *(const LAS u32x2*)(vp + 16);
;                 u32x4 wv; wv.x = lo.x; wv.y = lo.y; wv.z = hi.x; wv.w = hi.y;
;                 oacc[eb] = MFMA32(BITCAST(bf16x8, wv), pf, oacc[eb]);
;             }
.LBB0_824:
	v_lshlrev_b32_e32 v78, 6, v150
	v_add3_u32 v90, v157, v78, v158
	v_add_u32_e32 v91, 0xd800, v90
	ds_read2_b64 v[78:81], v91 offset1:2
	s_mov_b32 s6, 0xffff0000
	v_cvt_pk_bf16_f32 v85, v189, v191
	v_cvt_pk_bf16_f32 v84, v186, v190
	v_cvt_pk_bf16_f32 v83, v184, v188
	v_cvt_pk_bf16_f32 v82, v183, v185
	s_waitcnt lgkmcnt(0)
	s_nop 0
	v_mfma_f32_32x32x16_bf16 v[46:61], v[78:81], v[82:85], v[46:61]
	v_add_u32_e32 v78, 0x6100, v90
	v_add_u32_e32 v90, 0xd800, v78
	ds_read2_b64 v[78:81], v90 offset1:2
	ds_read2_b64 v[86:89], v91 offset0:4 offset1:6
	s_waitcnt lgkmcnt(1)
	v_mfma_f32_32x32x16_bf16 v[62:77], v[78:81], v[82:85], v[62:77]
	v_cvt_pk_bf16_f32 v81, v180, v182
	v_cvt_pk_bf16_f32 v80, v178, v181
	v_cvt_pk_bf16_f32 v79, v176, v179
	v_cvt_pk_bf16_f32 v78, v175, v177
	ds_read2_b64 v[82:85], v90 offset0:4 offset1:6
	s_waitcnt lgkmcnt(1)
	v_mfma_f32_32x32x16_bf16 v[46:61], v[86:89], v[78:81], v[46:61]
	s_waitcnt lgkmcnt(0)
	v_mfma_f32_32x32x16_bf16 v[62:77], v[82:85], v[78:81], v[62:77]
	s_or_b64 exec, exec, s[2:3]
	s_and_saveexec_b64 s[2:3], s[34:35]
	s_cbranch_execnz .LBB0_832

; #define LAS __attribute__((address_space(3)))
; #define MFMA32(a, b, c) __builtin_amdgcn_mfma_f32_32x32x16_bf16((a), (b), (c), 0, 0, 0)
; DEV unsigned pk2(float lo, float hi) { return (unsigned)f2bf(lo) | ((unsigned)f2bf(hi) << 16); }
; DEV void attn_compute(const AttnU& a, const bf16x8 (&qf)[4], int tq, bf16_t* OG, float* LSE, LAS unsigned char* lds, int tid) {
;     ...
;     for (int sb = 0; sb < 5; ++sb) {
;         if (!vb[sb]) continue;
; #pragma unroll
;         for (int s2 = 0; s2 < 2; ++s2) {
;             u32x4 w;
;             w.x = pk2(s[sb][8 * s2 + 0], s[sb][8 * s2 + 1]); w.y = pk2(s[sb][8 * s2 + 2], s[sb][8 * s2 + 3]);
;             w.z = pk2(s[sb][8 * s2 + 4], s[sb][8 * s2 + 5]); w.w = pk2(s[sb][8 * s2 + 6], s[sb][8 * s2 + 7]);
;             const bf16x8 pf = BITCAST(bf16x8, w);
; #pragma unroll
;             for (int eb = 0; eb < 2; ++eb) {
;                 const LAS unsigned char* vp = lds + AT_V_OFF + (32 * eb + n) * AT_VP + (32 * (wave + sb) + 16 * s2 + 4 * hl) * 2;
;                 const u32x2 lo = *(const LAS u32x2*)vp, hi = *(const LAS u32x2*)(vp + 16);
;                 u32x4 wv; wv.x = lo.x; wv.y = lo.y; wv.z = hi.x; wv.w = hi.y;
;                 oacc[eb] = MFMA32(BITCAST(bf16x8, wv), pf, oacc[eb]);
;             }
.LBB0_830:
	v_lshlrev_b32_e32 v46, 6, v149
	v_add3_u32 v58, v157, v46, v158
	v_add_u32_e32 v59, 0xd800, v58
	ds_read2_b64 v[46:49], v59 offset1:2
	s_mov_b32 s6, 0xffff0000
	v_cvt_pk_bf16_f32 v53, v212, v214
	v_cvt_pk_bf16_f32 v52, v210, v213
	v_cvt_pk_bf16_f32 v51, v209, v211
	v_cvt_pk_bf16_f32 v50, v208, v207
	s_waitcnt lgkmcnt(0)
	s_nop 0
	v_mfma_f32_32x32x16_bf16 v[78:93], v[46:49], v[50:53], v[78:93]
	v_add_u32_e32 v46, 0x6100, v58
	v_add_u32_e32 v58, 0xd800, v46
	ds_read2_b64 v[46:49], v58 offset1:2
	ds_read2_b64 v[54:57], v59 offset0:4 offset1:6
	s_waitcnt lgkmcnt(1)
	v_mfma_f32_32x32x16_bf16 v[94:109], v[46:49], v[50:53], v[94:109]
	v_cvt_pk_bf16_f32 v49, v202, v205
	v_cvt_pk_bf16_f32 v48, v199, v203
	v_cvt_pk_bf16_f32 v47, v197, v200
	v_cvt_pk_bf16_f32 v46, v194, v198
	ds_read2_b64 v[50:53], v58 offset0:4 offset1:6
	s_waitcnt lgkmcnt(1)
	v_mfma_f32_32x32x16_bf16 v[78:93], v[54:57], v[46:49], v[78:93]
	s_waitcnt lgkmcnt(0)
	v_mfma_f32_32x32x16_bf16 v[94:109], v[50:53], v[46:49], v[94:109]
	s_nop 9
	v_mov_b64_e32 v[46:47], v[78:79]
	v_mov_b64_e32 v[48:49], v[80:81]
	v_mov_b64_e32 v[50:51], v[82:83]
	v_mov_b64_e32 v[52:53], v[84:85]
	v_mov_b64_e32 v[54:55], v[86:87]
	v_mov_b64_e32 v[56:57], v[88:89]
	v_mov_b64_e32 v[58:59], v[90:91]
	v_mov_b64_e32 v[60:61], v[92:93]
	v_mov_b64_e32 v[62:63], v[94:95]
	v_mov_b64_e32 v[64:65], v[96:97]
	v_mov_b64_e32 v[66:67], v[98:99]
	v_mov_b64_e32 v[68:69], v[100:101]
	v_mov_b64_e32 v[70:71], v[102:103]
	v_mov_b64_e32 v[72:73], v[104:105]
	v_mov_b64_e32 v[74:75], v[106:107]
	v_mov_b64_e32 v[76:77], v[108:109]
	s_or_b64 exec, exec, s[2:3]
	s_and_saveexec_b64 s[2:3], s[30:31]
	s_cbranch_execnz .LBB0_824

; #define LAS __attribute__((address_space(3)))
; #define MFMA32(a, b, c) __builtin_amdgcn_mfma_f32_32x32x16_bf16((a), (b), (c), 0, 0, 0)
; DEV unsigned pk2(float lo, float hi) { return (unsigned)f2bf(lo) | ((unsigned)f2bf(hi) << 16); }
; DEV void attn_compute(const AttnU& a, const bf16x8 (&qf)[4], int tq, bf16_t* OG, float* LSE, LAS unsigned char* lds, int tid) {
;     ...
;     for (int sb = 0; sb < 5; ++sb) {
;         if (!vb[sb]) continue;
; #pragma unroll
;         for (int s2 = 0; s2 < 2; ++s2) {
;             u32x4 w;
;             w.x = pk2(s[sb][8 * s2 + 0], s[sb][8 * s2 + 1]); w.y = pk2(s[sb][8 * s2 + 2], s[sb][8 * s2 + 3]);
;             w.z = pk2(s[sb][8 * s2 + 4], s[sb][8 * s2 + 5]); w.w = pk2(s[sb][8 * s2 + 6], s[sb][8 * s2 + 7]);
;             const bf16x8 pf = BITCAST(bf16x8, w);
; #pragma unroll
;             for (int eb = 0; eb < 2; ++eb) {
;                 const LAS unsigned char* vp = lds + AT_V_OFF + (32 * eb + n) * AT_VP + (32 * (wave + sb) + 16 * s2 + 4 * hl) * 2;
;                 const u32x2 lo = *(const LAS u32x2*)vp, hi = *(const LAS u32x2*)(vp + 16);
;                 u32x4 wv; wv.x = lo.x; wv.y = lo.y; wv.z = hi.x; wv.w = hi.y;
;                 oacc[eb] = MFMA32(BITCAST(bf16x8, wv), pf, oacc[eb]);
;             }
.LBB0_832:
	v_lshlrev_b32_e32 v78, 6, v151
	v_add3_u32 v90, v157, v78, v158
	v_add_u32_e32 v91, 0xd800, v90
	ds_read2_b64 v[78:81], v91 offset1:2
	s_mov_b32 s6, 0xffff0000
	v_cvt_pk_bf16_f32 v85, v172, v174
	v_cvt_pk_bf16_f32 v84, v170, v173
	v_cvt_pk_bf16_f32 v83, v168, v171
	v_cvt_pk_bf16_f32 v82, v167, v169
	s_waitcnt lgkmcnt(0)
	s_nop 0
	v_mfma_f32_32x32x16_bf16 v[46:61], v[78:81], v[82:85], v[46:61]
	v_add_u32_e32 v78, 0x6100, v90
	v_add_u32_e32 v90, 0xd800, v78
	ds_read2_b64 v[78:81], v90 offset1:2
	ds_read2_b64 v[86:89], v91 offset0:4 offset1:6
	s_waitcnt lgkmcnt(1)
	v_mfma_f32_32x32x16_bf16 v[62:77], v[78:81], v[82:85], v[62:77]
	v_cvt_pk_bf16_f32 v81, v164, v166
	v_cvt_pk_bf16_f32 v80, v162, v165
	v_cvt_pk_bf16_f32 v79, v160, v163
	v_cvt_pk_bf16_f32 v78, v159, v161
	ds_read2_b64 v[82:85], v90 offset0:4 offset1:6
	s_waitcnt lgkmcnt(1)
	v_mfma_f32_32x32x16_bf16 v[46:61], v[86:89], v[78:81], v[46:61]
	s_waitcnt lgkmcnt(0)
	v_mfma_f32_32x32x16_bf16 v[62:77], v[82:85], v[78:81], v[62:77]
	s_or_b64 exec, exec, s[2:3]
	s_and_saveexec_b64 s[2:3], s[36:37]
	s_cbranch_execnz .LBB0_826
	s_branch .LBB0_827
